# gate/up GEMM phases: one static s_setprio 1 for waves 4-7 at phase entry (reset at phase exit), per-cluster toggles already removed
# baseline (speedup 1.0000x reference)
.LBB0_684:
	s_or_b64 exec, exec, s[0:1]
	s_mov_b64 s[4:5], s[36:37]
	s_mov_b64 s[0:1], s[94:95]
	s_waitcnt lgkmcnt(0)
	s_barrier
	v_readfirstlane_b32 s99, v154
	s_nop 3
	s_lshr_b32 s99, s99, 8
	s_cmp_eq_u32 s99, 1
	s_cbranch_scc0 .Lprio_a
	s_setprio 1
.Lprio_a:
	v_readlane_b32 s2, v255, 36
	v_readlane_b32 s0, v255, 0
	s_add_i32 s0, s0, s84
	s_ashr_i32 s1, s0, 31
	s_abs_i32 s0, s0
	s_mul_hi_u32 s2, s0, s2
	s_mul_i32 s2, s2, s60
	s_sub_i32 s0, s0, s2
	s_sub_i32 s2, s0, s60
	s_cmp_ge_u32 s0, s60
	s_cselect_b32 s0, s2, s0
	s_sub_i32 s2, s0, s60
	s_cmp_ge_u32 s0, s60
	s_cselect_b32 s0, s2, s0
	s_xor_b32 s0, s0, s1
	s_sub_i32 s2, s0, s1
	s_cmpk_gt_i32 s2, 0xb57
	s_cbranch_scc1 .LBB0_695
	s_add_u32 s44, s4, 0x86c4000
	s_addc_u32 s45, s5, 0
	s_add_u32 s6, s4, 0xc8c4000
	s_addc_u32 s7, s5, 0
	s_add_u32 s46, s4, 0x13c4000
	s_addc_u32 s47, s5, 0
	s_ashr_i32 s48, s2, 31
	s_lshr_b32 s0, s48, 29
	s_add_i32 s0, s2, s0
	s_ashr_i32 s1, s0, 3
	s_and_b32 s0, s0, -8
	s_sub_i32 s0, s2, s0
	s_cmp_lt_i32 s0, 0
	s_movk_i32 s49, 0x16c
	s_cselect_b32 s8, s49, 0x16b
	s_mul_i32 s0, s8, s0
	s_add_i32 s0, s0, s1
	s_mul_hi_i32 s1, s0, 0x2e8ba2e9
	s_lshr_b32 s8, s1, 31
	s_ashr_i32 s1, s1, 5
	s_add_i32 s1, s1, s8
	s_mul_i32 s8, s1, 0xb0
	s_lshl_b32 s9, s1, 3
	s_sub_i32 s8, s0, s8
	s_sub_i32 s0, 0x84, s9
	s_min_u32 s10, s0, 8
	v_cvt_f32_ubyte0_e32 v1, s10
	v_cvt_f32_i32_e32 v0, s8
	v_rcp_iflag_f32_e32 v2, v1
	s_ashr_i32 s0, s8, 30
	s_or_b32 s11, s0, 1
	s_mov_b32 s50, 0
	v_mul_f32_e32 v2, v0, v2
	v_trunc_f32_e32 v2, v2
	v_fma_f32 v0, -v2, v1, v0
	v_cvt_i32_f32_e32 v2, v2
	v_cmp_ge_f32_e64 s[0:1], |v0|, v1
	s_and_b64 s[0:1], s[0:1], exec
	s_cselect_b32 s0, s11, 0
	v_readfirstlane_b32 s1, v2
	s_add_i32 s0, s1, s0
	s_sext_i32_i16 s56, s0
	s_mul_i32 s0, s0, s10
	s_sub_i32 s0, s8, s0
	s_sext_i32_i16 s0, s0
	s_add_i32 s38, s9, s0
	v_mov_b64_e32 v[128:129], 0xb57
	s_mov_b64 s[8:9], 0x80
	s_movk_i32 s51, 0x3c0
	s_mov_b64 s[10:11], 0x8704080
	s_mov_b64 s[12:13], 0x13c4100
	s_mov_b64 s[14:15], 0x86c4100
	s_mov_b64 s[16:17], 0x1404100
	s_mov_b64 s[18:19], 0x8704100
	s_mov_b64 s[20:21], 0x13c4180
	s_mov_b64 s[22:23], 0x86c4180
	s_mov_b64 s[24:25], 0x1404180
	s_mov_b64 s[26:27], 0x100
	s_mov_b64 s[28:29], 0x780
	s_movk_i32 s52, 0x100
	s_movk_i32 s53, 0x1600
	v_mov_b32_e32 v142, 1
	s_branch .LBB0_687

.LBB0_695:
	s_setprio 0
	s_getreg_b32 s2, hwreg(HW_REG_XCC_ID, 0, 4)
	s_waitcnt vmcnt(0)
	v_mov_b32_e32 v0, v154
	s_waitcnt vmcnt(0) lgkmcnt(0)
	s_barrier
	s_nop 0
	v_cmp_eq_u32_e32 vcc, 0, v0
	s_and_saveexec_b64 s[0:1], vcc
	s_cbranch_execz .LBB0_747
	s_add_i32 s4, 0, 0x20010
	v_mov_b32_e32 v0, s4
	s_waitcnt vmcnt(0) expcnt(0) lgkmcnt(0)
	ds_read_b32 v2, v0
	s_add_i32 s4, 0, 0x20014
	v_mov_b32_e32 v0, s4
	ds_read_b32 v0, v0
	s_and_b32 s2, s2, 15
	s_waitcnt lgkmcnt(1)
	v_cmp_ne_u32_e32 vcc, 0, v2
	s_cbranch_vccnz .LBB0_711
	v_readlane_b32 s4, v255, 1
	s_mul_i32 s18, s85, s4
	s_add_u32 s4, s36, 0x1000
	s_addc_u32 s5, s37, 0
	s_add_u32 s6, s36, 0x1100
	s_addc_u32 s7, s37, 0
	s_add_u32 s8, s36, 0x1200
	s_addc_u32 s9, s37, 0
	s_add_u32 s10, s36, 0x1300
	s_mul_i32 s18, s18, s84
	s_addc_u32 s11, s37, 0
	s_mov_b32 s19, 1
	v_mov_b32_e32 v16, 0
	s_branch .LBB0_699

.Lprio_b:
	v_readlane_b32 s2, v255, 36
	v_readlane_b32 s0, v255, 0
	s_add_i32 s0, s0, s84
	s_ashr_i32 s1, s0, 31
	s_abs_i32 s0, s0
	s_mul_hi_u32 s2, s0, s2
	s_mul_i32 s2, s2, s60
	s_sub_i32 s0, s0, s2
	s_sub_i32 s2, s0, s60
	s_cmp_ge_u32 s0, s60
	s_cselect_b32 s0, s2, s0
	s_sub_i32 s2, s0, s60
	s_cmp_ge_u32 s0, s60
	s_cselect_b32 s0, s2, s0
	s_xor_b32 s0, s0, s1
	s_sub_i32 s2, s0, s1
	s_cmpk_gt_i32 s2, 0xb57
	s_cbranch_scc1 .LBB0_1809
	s_add_u32 s44, s4, 0x86c4000
	s_addc_u32 s45, s5, 0
	s_add_u32 s6, s4, 0xc8c4000
	s_addc_u32 s7, s5, 0
	s_add_u32 s46, s4, 0x1ec4000
	s_addc_u32 s47, s5, 0
	s_ashr_i32 s48, s2, 31
	s_lshr_b32 s0, s48, 29
	s_add_i32 s0, s2, s0
	s_ashr_i32 s1, s0, 3
	s_and_b32 s0, s0, -8
	s_sub_i32 s0, s2, s0
	s_cmp_lt_i32 s0, 0
	s_movk_i32 s49, 0x16c
	s_cselect_b32 s8, s49, 0x16b
	s_mul_i32 s0, s8, s0
	s_add_i32 s0, s0, s1
	s_mul_hi_i32 s1, s0, 0x2e8ba2e9
	s_lshr_b32 s8, s1, 31
	s_ashr_i32 s1, s1, 5
	s_add_i32 s1, s1, s8
	s_mul_i32 s8, s1, 0xb0
	s_lshl_b32 s9, s1, 3
	s_sub_i32 s8, s0, s8
	s_sub_i32 s0, 0x84, s9
	s_min_u32 s10, s0, 8
	v_cvt_f32_ubyte0_e32 v1, s10
	v_cvt_f32_i32_e32 v0, s8
	v_rcp_iflag_f32_e32 v2, v1
	s_ashr_i32 s0, s8, 30
	s_or_b32 s11, s0, 1
	s_mov_b32 s50, 0
	v_mul_f32_e32 v2, v0, v2
	v_trunc_f32_e32 v2, v2
	v_fma_f32 v0, -v2, v1, v0
	v_cvt_i32_f32_e32 v2, v2
	v_cmp_ge_f32_e64 s[0:1], |v0|, v1
	s_and_b64 s[0:1], s[0:1], exec
	s_cselect_b32 s0, s11, 0
	v_readfirstlane_b32 s1, v2
	s_add_i32 s0, s1, s0
	s_sext_i32_i16 s56, s0
	s_mul_i32 s0, s0, s10
	s_sub_i32 s0, s8, s0
	s_sext_i32_i16 s0, s0
	s_add_i32 s38, s9, s0
	v_mov_b64_e32 v[128:129], 0xb57
	s_mov_b64 s[8:9], 0x80
	s_movk_i32 s51, 0x3c0
	s_mov_b64 s[10:11], 0x8704080
	s_mov_b64 s[12:13], 0x1ec4100
	s_mov_b64 s[14:15], 0x86c4100
	s_mov_b64 s[16:17], 0x1f04100
	s_mov_b64 s[18:19], 0x8704100
	s_mov_b64 s[20:21], 0x1ec4180
	s_mov_b64 s[22:23], 0x86c4180
	s_mov_b64 s[24:25], 0x1f04180
	s_mov_b64 s[26:27], 0x100
	s_mov_b64 s[28:29], 0x780
	s_movk_i32 s52, 0x100
	s_movk_i32 s53, 0x1600
	v_mov_b32_e32 v142, 1
	s_branch .LBB0_1801
